# phase-4 residual epilogue re-written: 16 x-loads in flight with counted waits instead of 32 serialized load-wait-add-store rounds
# speedup vs baseline: 1.0433x; 1.0010x over previous
.LBB0_1190:
	s_or_b64 exec, exec, s[30:31]
	v_and_b32_e32 v128, 15, v141
	s_lshl_b32 s4, s28, 8
	v_and_b32_e32 v129, 0x60, v142
	v_or3_b32 v128, v129, s4, v128
	v_ashrrev_i32_e32 v129, 2, v141
	v_and_b32_e32 v129, 0xffffffc0, v129
	v_lshl_add_u32 v129, s55, 8, v129
	v_lshrrev_b32_e32 v130, 2, v141
	v_and_or_b32 v130, v130, 12, v129
	v_ashrrev_i32_e32 v131, 31, v130
	v_lshlrev_b64 v[130:131], 2, v[130:131]
	v_mov_b32_e32 v228, v128
	v_ashrrev_i32_e32 v229, 31, v228
	v_lshlrev_b64 v[230:231], 12, v[228:229]
	v_lshl_add_u64 v[232:233], s[78:79], 0, v[230:231]
	v_lshl_add_u64 v[232:233], v[232:233], 0, s[24:25]
	v_lshl_add_u64 v[234:235], s[76:77], 0, v[230:231]
	v_cmp_gt_i32_e32 vcc, s49, v228
	v_lshl_add_u64 v[220:221], s[26:27], 0, v[230:231]
	v_lshl_add_u64 v[220:221], v[220:221], 0, v[130:131]
	v_cndmask_b32_e32 v232, v232, v234, vcc
	v_cndmask_b32_e32 v233, v233, v235, vcc
	v_lshl_add_u64 v[212:213], v[232:233], 0, v[130:131]
	v_or_b32_e32 v228, 0x10, v128
	v_ashrrev_i32_e32 v229, 31, v228
	v_lshlrev_b64 v[230:231], 12, v[228:229]
	v_lshl_add_u64 v[232:233], s[78:79], 0, v[230:231]
	v_lshl_add_u64 v[232:233], v[232:233], 0, s[24:25]
	v_lshl_add_u64 v[234:235], s[76:77], 0, v[230:231]
	v_cmp_gt_i32_e32 vcc, s49, v228
	v_lshl_add_u64 v[222:223], s[26:27], 0, v[230:231]
	v_lshl_add_u64 v[222:223], v[222:223], 0, v[130:131]
	v_cndmask_b32_e32 v232, v232, v234, vcc
	v_cndmask_b32_e32 v233, v233, v235, vcc
	v_lshl_add_u64 v[214:215], v[232:233], 0, v[130:131]
	v_or_b32_e32 v228, 0x80, v128
	v_ashrrev_i32_e32 v229, 31, v228
	v_lshlrev_b64 v[230:231], 12, v[228:229]
	v_lshl_add_u64 v[232:233], s[78:79], 0, v[230:231]
	v_lshl_add_u64 v[232:233], v[232:233], 0, s[24:25]
	v_lshl_add_u64 v[234:235], s[76:77], 0, v[230:231]
	v_cmp_gt_i32_e32 vcc, s49, v228
	v_lshl_add_u64 v[224:225], s[26:27], 0, v[230:231]
	v_lshl_add_u64 v[224:225], v[224:225], 0, v[130:131]
	v_cndmask_b32_e32 v232, v232, v234, vcc
	v_cndmask_b32_e32 v233, v233, v235, vcc
	v_lshl_add_u64 v[216:217], v[232:233], 0, v[130:131]
	v_or_b32_e32 v228, 0x90, v128
	v_ashrrev_i32_e32 v229, 31, v228
	v_lshlrev_b64 v[230:231], 12, v[228:229]
	v_lshl_add_u64 v[232:233], s[78:79], 0, v[230:231]
	v_lshl_add_u64 v[232:233], v[232:233], 0, s[24:25]
	v_lshl_add_u64 v[234:235], s[76:77], 0, v[230:231]
	v_cmp_gt_i32_e32 vcc, s49, v228
	v_lshl_add_u64 v[226:227], s[26:27], 0, v[230:231]
	v_lshl_add_u64 v[226:227], v[226:227], 0, v[130:131]
	v_cndmask_b32_e32 v232, v232, v234, vcc
	v_cndmask_b32_e32 v233, v233, v235, vcc
	v_lshl_add_u64 v[218:219], v[232:233], 0, v[130:131]
	global_load_dwordx4 v[144:147], v[212:213], off
	global_load_dwordx4 v[148:151], v[212:213], off offset:64
	global_load_dwordx4 v[152:155], v[212:213], off offset:128
	global_load_dwordx4 v[156:159], v[212:213], off offset:192
	global_load_dwordx4 v[160:163], v[212:213], off offset:512
	global_load_dwordx4 v[164:167], v[212:213], off offset:576
	global_load_dwordx4 v[168:171], v[212:213], off offset:640
	global_load_dwordx4 v[172:175], v[212:213], off offset:704
	global_load_dwordx4 v[176:179], v[214:215], off
	global_load_dwordx4 v[180:183], v[214:215], off offset:64
	global_load_dwordx4 v[184:187], v[214:215], off offset:128
	global_load_dwordx4 v[188:191], v[214:215], off offset:192
	global_load_dwordx4 v[196:199], v[214:215], off offset:512
	global_load_dwordx4 v[200:203], v[214:215], off offset:576
	global_load_dwordx4 v[204:207], v[214:215], off offset:640
	global_load_dwordx4 v[208:211], v[214:215], off offset:704
	s_waitcnt vmcnt(15)
	v_pk_add_f32 v[116:117], v[116:117], v[144:145]
	v_pk_add_f32 v[118:119], v[118:119], v[146:147]
	global_store_dwordx4 v[220:221], v[116:119], off
	global_load_dwordx4 v[144:147], v[216:217], off
	s_waitcnt vmcnt(16)
	v_pk_add_f32 v[108:109], v[108:109], v[148:149]
	v_pk_add_f32 v[110:111], v[110:111], v[150:151]
	global_store_dwordx4 v[220:221], v[108:111], off offset:64
	global_load_dwordx4 v[148:151], v[216:217], off offset:64
	s_waitcnt vmcnt(17)
	v_pk_add_f32 v[104:105], v[104:105], v[152:153]
	v_pk_add_f32 v[106:107], v[106:107], v[154:155]
	global_store_dwordx4 v[220:221], v[104:107], off offset:128
	global_load_dwordx4 v[152:155], v[216:217], off offset:128
	s_waitcnt vmcnt(18)
	v_pk_add_f32 v[100:101], v[100:101], v[156:157]
	v_pk_add_f32 v[102:103], v[102:103], v[158:159]
	global_store_dwordx4 v[220:221], v[100:103], off offset:192
	global_load_dwordx4 v[156:159], v[216:217], off offset:192
	s_waitcnt vmcnt(19)
	v_pk_add_f32 v[124:125], v[124:125], v[160:161]
	v_pk_add_f32 v[126:127], v[126:127], v[162:163]
	global_store_dwordx4 v[220:221], v[124:127], off offset:512
	global_load_dwordx4 v[160:163], v[216:217], off offset:512
	s_waitcnt vmcnt(20)
	v_pk_add_f32 v[120:121], v[120:121], v[164:165]
	v_pk_add_f32 v[122:123], v[122:123], v[166:167]
	global_store_dwordx4 v[220:221], v[120:123], off offset:576
	global_load_dwordx4 v[164:167], v[216:217], off offset:576
	s_waitcnt vmcnt(21)
	v_pk_add_f32 v[112:113], v[112:113], v[168:169]
	v_pk_add_f32 v[114:115], v[114:115], v[170:171]
	global_store_dwordx4 v[220:221], v[112:115], off offset:640
	global_load_dwordx4 v[168:171], v[216:217], off offset:640
	s_waitcnt vmcnt(22)
	v_pk_add_f32 v[96:97], v[96:97], v[172:173]
	v_pk_add_f32 v[98:99], v[98:99], v[174:175]
	global_store_dwordx4 v[220:221], v[96:99], off offset:704
	global_load_dwordx4 v[172:175], v[216:217], off offset:704
	s_waitcnt vmcnt(23)
	v_pk_add_f32 v[84:85], v[84:85], v[176:177]
	v_pk_add_f32 v[86:87], v[86:87], v[178:179]
	global_store_dwordx4 v[222:223], v[84:87], off
	global_load_dwordx4 v[176:179], v[218:219], off
	s_waitcnt vmcnt(24)
	v_pk_add_f32 v[76:77], v[76:77], v[180:181]
	v_pk_add_f32 v[78:79], v[78:79], v[182:183]
	global_store_dwordx4 v[222:223], v[76:79], off offset:64
	global_load_dwordx4 v[180:183], v[218:219], off offset:64
	s_waitcnt vmcnt(25)
	v_pk_add_f32 v[72:73], v[72:73], v[184:185]
	v_pk_add_f32 v[74:75], v[74:75], v[186:187]
	global_store_dwordx4 v[222:223], v[72:75], off offset:128
	global_load_dwordx4 v[184:187], v[218:219], off offset:128
	s_waitcnt vmcnt(26)
	v_pk_add_f32 v[68:69], v[68:69], v[188:189]
	v_pk_add_f32 v[70:71], v[70:71], v[190:191]
	global_store_dwordx4 v[222:223], v[68:71], off offset:192
	global_load_dwordx4 v[188:191], v[218:219], off offset:192
	s_waitcnt vmcnt(27)
	v_pk_add_f32 v[92:93], v[92:93], v[196:197]
	v_pk_add_f32 v[94:95], v[94:95], v[198:199]
	global_store_dwordx4 v[222:223], v[92:95], off offset:512
	global_load_dwordx4 v[196:199], v[218:219], off offset:512
	s_waitcnt vmcnt(28)
	v_pk_add_f32 v[88:89], v[88:89], v[200:201]
	v_pk_add_f32 v[90:91], v[90:91], v[202:203]
	global_store_dwordx4 v[222:223], v[88:91], off offset:576
	global_load_dwordx4 v[200:203], v[218:219], off offset:576
	s_waitcnt vmcnt(29)
	v_pk_add_f32 v[80:81], v[80:81], v[204:205]
	v_pk_add_f32 v[82:83], v[82:83], v[206:207]
	global_store_dwordx4 v[222:223], v[80:83], off offset:640
	global_load_dwordx4 v[204:207], v[218:219], off offset:640
	s_waitcnt vmcnt(30)
	v_pk_add_f32 v[64:65], v[64:65], v[208:209]
	v_pk_add_f32 v[66:67], v[66:67], v[210:211]
	global_store_dwordx4 v[222:223], v[64:67], off offset:704
	global_load_dwordx4 v[208:211], v[218:219], off offset:704
	s_waitcnt vmcnt(30)
	v_pk_add_f32 v[60:61], v[60:61], v[144:145]
	v_pk_add_f32 v[62:63], v[62:63], v[146:147]
	global_store_dwordx4 v[224:225], v[60:63], off
	s_waitcnt vmcnt(29)
	v_pk_add_f32 v[52:53], v[52:53], v[148:149]
	v_pk_add_f32 v[54:55], v[54:55], v[150:151]
	global_store_dwordx4 v[224:225], v[52:55], off offset:64
	s_waitcnt vmcnt(28)
	v_pk_add_f32 v[44:45], v[44:45], v[152:153]
	v_pk_add_f32 v[46:47], v[46:47], v[154:155]
	global_store_dwordx4 v[224:225], v[44:47], off offset:128
	s_waitcnt vmcnt(27)
	v_pk_add_f32 v[36:37], v[36:37], v[156:157]
	v_pk_add_f32 v[38:39], v[38:39], v[158:159]
	global_store_dwordx4 v[224:225], v[36:39], off offset:192
	s_waitcnt vmcnt(26)
	v_pk_add_f32 v[56:57], v[56:57], v[160:161]
	v_pk_add_f32 v[58:59], v[58:59], v[162:163]
	global_store_dwordx4 v[224:225], v[56:59], off offset:512
	s_waitcnt vmcnt(25)
	v_pk_add_f32 v[48:49], v[48:49], v[164:165]
	v_pk_add_f32 v[50:51], v[50:51], v[166:167]
	global_store_dwordx4 v[224:225], v[48:51], off offset:576
	s_waitcnt vmcnt(24)
	v_pk_add_f32 v[40:41], v[40:41], v[168:169]
	v_pk_add_f32 v[42:43], v[42:43], v[170:171]
	global_store_dwordx4 v[224:225], v[40:43], off offset:640
	s_waitcnt vmcnt(23)
	v_pk_add_f32 v[32:33], v[32:33], v[172:173]
	v_pk_add_f32 v[34:35], v[34:35], v[174:175]
	global_store_dwordx4 v[224:225], v[32:35], off offset:704
	s_waitcnt vmcnt(22)
	v_pk_add_f32 v[28:29], v[28:29], v[176:177]
	v_pk_add_f32 v[30:31], v[30:31], v[178:179]
	global_store_dwordx4 v[226:227], v[28:31], off
	s_waitcnt vmcnt(21)
	v_pk_add_f32 v[20:21], v[20:21], v[180:181]
	v_pk_add_f32 v[22:23], v[22:23], v[182:183]
	global_store_dwordx4 v[226:227], v[20:23], off offset:64
	s_waitcnt vmcnt(20)
	v_pk_add_f32 v[12:13], v[12:13], v[184:185]
	v_pk_add_f32 v[14:15], v[14:15], v[186:187]
	global_store_dwordx4 v[226:227], v[12:15], off offset:128
	s_waitcnt vmcnt(19)
	v_pk_add_f32 v[4:5], v[4:5], v[188:189]
	v_pk_add_f32 v[6:7], v[6:7], v[190:191]
	global_store_dwordx4 v[226:227], v[4:7], off offset:192
	s_waitcnt vmcnt(18)
	v_pk_add_f32 v[24:25], v[24:25], v[196:197]
	v_pk_add_f32 v[26:27], v[26:27], v[198:199]
	global_store_dwordx4 v[226:227], v[24:27], off offset:512
	s_waitcnt vmcnt(17)
	v_pk_add_f32 v[16:17], v[16:17], v[200:201]
	v_pk_add_f32 v[18:19], v[18:19], v[202:203]
	global_store_dwordx4 v[226:227], v[16:19], off offset:576
	s_waitcnt vmcnt(16)
	v_pk_add_f32 v[8:9], v[8:9], v[204:205]
	v_pk_add_f32 v[10:11], v[10:11], v[206:207]
	global_store_dwordx4 v[226:227], v[8:11], off offset:640
	s_waitcnt vmcnt(15)
	v_pk_add_f32 v[0:1], v[0:1], v[208:209]
	v_pk_add_f32 v[2:3], v[2:3], v[210:211]
	global_store_dwordx4 v[226:227], v[0:3], off offset:704
	s_mov_b64 s[26:27], exec
	v_readlane_b32 s28, v255, 10
	v_readlane_b32 s29, v255, 11
	s_and_b64 s[28:29], s[26:27], s[28:29]
	s_mov_b64 exec, s[28:29]
	s_cbranch_execz .LBB0_1183
	s_mov_b64 s[28:29], exec
	v_mbcnt_lo_u32_b32 v0, s28, 0
	v_mbcnt_hi_u32_b32 v0, s29, v0
	v_cmp_eq_u32_e32 vcc, 0, v0
	s_and_b64 s[30:31], exec, vcc
	s_mov_b64 exec, s[30:31]
	s_cbranch_execz .LBB0_1183
	s_bcnt1_i32_b64 s4, s[28:29]
	v_mov_b32_e32 v0, s4
	global_atomic_add v140, v0, s[0:1]
	s_branch .LBB0_1183
